# ffn2 K loop 3-deep: second barrier after ds_reads frees the stage, DMA(k+2) issued there (2 LDS stages + registers)
# baseline (speedup 1.0000x reference)
.LBB0_131:
	s_and_b32 s14, s16, 0x8000
	v_add_u32_e32 v122, s14, v88
	v_or_b32_e32 v138, s14, v89
	v_add_u32_e32 v102, v122, v86
	v_add_u32_e32 v118, v138, v86
	v_add_u32_e32 v134, v122, v87
	v_add_u32_e32 v146, v138, v87
	ds_read_b128 v[90:93], v102
	ds_read_b128 v[94:97], v102 offset:2048
	ds_read_b128 v[98:101], v102 offset:4096
	ds_read_b128 v[102:105], v102 offset:6144
	ds_read_b128 v[106:109], v118 offset:16384
	ds_read_b128 v[110:113], v118 offset:18432
	ds_read_b128 v[114:117], v118 offset:20480
	ds_read_b128 v[118:121], v118 offset:22528
	ds_read_b128 v[122:125], v134
	ds_read_b128 v[126:129], v134 offset:2048
	ds_read_b128 v[130:133], v134 offset:4096
	ds_read_b128 v[134:137], v134 offset:6144
	ds_read_b128 v[138:141], v146 offset:16384
	ds_read_b128 v[142:145], v146 offset:18432
	ds_read_b128 v[150:153], v146 offset:20480
	ds_read_b128 v[154:157], v146 offset:22528
	s_waitcnt lgkmcnt(0)
	s_barrier
	s_cmp_gt_u32 s17, 61
	s_cbranch_scc1 .Lx3_tail
	s_and_b32 s14, s16, 0x8000
	v_add_u32_e32 v162, s14, v85
	s_lshl_b32 s15, s26, 1
	s_and_b32 s15, s15, 0x700
	v_readfirstlane_b32 s14, v162
	s_mov_b32 m0, s14
	s_add_u32 s14, s15, s28
	s_add_u32 s14, s14, 0x100
	s_and_b32 s14, s14, 0x1fff
	s_add_u32 s14, s14, 0x1201000
	s_mov_b32 s15, 0
	v_lshl_add_u64 v[162:163], v[82:83], 0, s[14:15]
	s_sub_u32 s14, s14, 0x800000
	v_lshl_add_u64 v[160:161], v[80:81], 0, s[14:15]
	global_load_lds_dwordx4 v[162:163], off
	s_add_u32 m0, m0, 0x1000
	v_lshl_add_u64 v[162:163], v[162:163], 0, s[40:41]
	global_load_lds_dwordx4 v[162:163], off
	s_add_u32 m0, m0, 0x1000
	v_lshl_add_u64 v[162:163], v[162:163], 0, s[40:41]
	global_load_lds_dwordx4 v[162:163], off
	s_add_u32 m0, m0, 0x1000
	v_lshl_add_u64 v[162:163], v[162:163], 0, s[40:41]
	global_load_lds_dwordx4 v[162:163], off
	s_add_u32 m0, m0, 0x1000
	s_nop 0
	global_load_lds_dwordx4 v[160:161], off
	s_add_u32 m0, m0, 0x1000
	v_lshl_add_u64 v[160:161], v[160:161], 0, s[40:41]
	global_load_lds_dwordx4 v[160:161], off
	s_add_u32 m0, m0, 0x1000
	v_lshl_add_u64 v[160:161], v[160:161], 0, s[40:41]
	global_load_lds_dwordx4 v[160:161], off
	s_add_u32 m0, m0, 0x1000
	v_lshl_add_u64 v[160:161], v[160:161], 0, s[40:41]
	global_load_lds_dwordx4 v[160:161], off
	s_branch .Lx3_mfma
.Lx3_tail:
	s_cmp_lg_u32 s17, 62
	s_cbranch_scc1 .Lx3_mfma
	s_andn2_b64 vcc, exec, s[30:31]
	s_cbranch_vccnz .Lx3_mfma
	v_readfirstlane_b32 s14, v85
	s_mov_b32 m0, s14
	s_nop 0
	global_load_lds_dwordx4 v[64:65], off
	s_add_u32 m0, m0, 0x1000
	s_nop 0
	global_load_lds_dwordx4 v[68:69], off
	s_add_u32 m0, m0, 0x1000
	s_nop 0
	global_load_lds_dwordx4 v[70:71], off
	s_add_u32 m0, m0, 0x1000
	s_nop 0
	global_load_lds_dwordx4 v[72:73], off
	s_add_u32 m0, m0, 0x1000
	s_nop 0
	global_load_lds_dwordx4 v[66:67], off
	s_add_u32 m0, m0, 0x1000
	s_nop 0
	global_load_lds_dwordx4 v[74:75], off
	s_add_u32 m0, m0, 0x1000
	s_nop 0
	global_load_lds_dwordx4 v[76:77], off
	s_add_u32 m0, m0, 0x1000
	s_nop 0
	global_load_lds_dwordx4 v[78:79], off
.Lx3_mfma:
	v_mfma_f32_16x16x32_bf16 v[52:55], v[90:93], v[106:109], v[52:55]
	s_add_i32 s16, s16, 0x8000
	s_add_u32 s28, s28, 0x80
	s_addc_u32 s29, s29, 0
	v_mfma_f32_16x16x32_bf16 v[48:51], v[90:93], v[110:113], v[48:51]
	s_add_i32 s17, s17, 1
	s_cmpk_lg_i32 s28, 0x2000
	v_mfma_f32_16x16x32_bf16 v[44:47], v[90:93], v[114:117], v[44:47]
	v_mfma_f32_16x16x32_bf16 v[40:43], v[90:93], v[118:121], v[40:43]
	v_mfma_f32_16x16x32_bf16 v[36:39], v[94:97], v[106:109], v[36:39]
	v_mfma_f32_16x16x32_bf16 v[32:35], v[94:97], v[110:113], v[32:35]
	v_mfma_f32_16x16x32_bf16 v[28:31], v[94:97], v[114:117], v[28:31]
	v_mfma_f32_16x16x32_bf16 v[24:27], v[94:97], v[118:121], v[24:27]
	v_mfma_f32_16x16x32_bf16 v[20:23], v[98:101], v[106:109], v[20:23]
	v_mfma_f32_16x16x32_bf16 v[16:19], v[98:101], v[110:113], v[16:19]
	v_mfma_f32_16x16x32_bf16 v[12:15], v[98:101], v[114:117], v[12:15]
	v_mfma_f32_16x16x32_bf16 v[8:11], v[98:101], v[118:121], v[8:11]
	v_mfma_f32_16x16x32_bf16 v[4:7], v[102:105], v[106:109], v[4:7]
	v_mfma_f32_16x16x32_bf16 v[0:3], v[102:105], v[110:113], v[0:3]
	v_mfma_f32_16x16x32_bf16 v[56:59], v[102:105], v[114:117], v[56:59]
	v_mfma_f32_16x16x32_bf16 v[60:63], v[102:105], v[118:121], v[60:63]
	v_mfma_f32_16x16x32_bf16 v[52:55], v[122:125], v[138:141], v[52:55]
	v_mfma_f32_16x16x32_bf16 v[48:51], v[122:125], v[142:145], v[48:51]
	v_mfma_f32_16x16x32_bf16 v[44:47], v[122:125], v[150:153], v[44:47]
	v_mfma_f32_16x16x32_bf16 v[40:43], v[122:125], v[154:157], v[40:43]
	v_mfma_f32_16x16x32_bf16 v[36:39], v[126:129], v[138:141], v[36:39]
	v_mfma_f32_16x16x32_bf16 v[32:35], v[126:129], v[142:145], v[32:35]
	v_mfma_f32_16x16x32_bf16 v[28:31], v[126:129], v[150:153], v[28:31]
	v_mfma_f32_16x16x32_bf16 v[24:27], v[126:129], v[154:157], v[24:27]
	v_mfma_f32_16x16x32_bf16 v[20:23], v[130:133], v[138:141], v[20:23]
	v_mfma_f32_16x16x32_bf16 v[16:19], v[130:133], v[142:145], v[16:19]
	v_mfma_f32_16x16x32_bf16 v[12:15], v[130:133], v[150:153], v[12:15]
	v_mfma_f32_16x16x32_bf16 v[8:11], v[130:133], v[154:157], v[8:11]
	v_mfma_f32_16x16x32_bf16 v[4:7], v[134:137], v[138:141], v[4:7]
	v_mfma_f32_16x16x32_bf16 v[0:3], v[134:137], v[142:145], v[0:3]
	v_mfma_f32_16x16x32_bf16 v[56:59], v[134:137], v[150:153], v[56:59]
	v_mfma_f32_16x16x32_bf16 v[60:63], v[134:137], v[154:157], v[60:63]
	s_cbranch_scc0 .LBB0_138
.LBB0_132:
	s_cmp_eq_u32 s17, 0
	s_cbranch_scc1 .Lx3_w0
	s_cmp_eq_u32 s17, 63
	s_cbranch_scc1 .Lx3_w0
	s_waitcnt vmcnt(8) lgkmcnt(0)
	s_barrier
	s_branch .LBB0_131
.Lx3_w0:
	s_waitcnt vmcnt(0) lgkmcnt(0)
	s_barrier
	s_cmp_lg_u32 s17, 0
	s_cbranch_scc1 .LBB0_131
	s_add_i32 s14, s16, 0x8000
	s_and_b32 s14, s14, 0x8000
	v_add_u32_e32 v92, s14, v85
	s_lshl_b32 s15, s26, 1
	s_and_b32 s15, s15, 0x700
	v_readfirstlane_b32 s14, v92
	s_mov_b32 m0, s14
	s_add_u32 s14, s15, s28
	s_add_u32 s14, s14, 0x80
	s_and_b32 s14, s14, 0x1fff
	s_add_u32 s14, s14, 0x1201000
	s_mov_b32 s15, 0
	v_lshl_add_u64 v[92:93], v[82:83], 0, s[14:15]
	s_sub_u32 s14, s14, 0x800000
	v_lshl_add_u64 v[90:91], v[80:81], 0, s[14:15]
	global_load_lds_dwordx4 v[92:93], off
	s_add_u32 m0, m0, 0x1000
	v_lshl_add_u64 v[92:93], v[92:93], 0, s[40:41]
	global_load_lds_dwordx4 v[92:93], off
	s_add_u32 m0, m0, 0x1000
	v_lshl_add_u64 v[92:93], v[92:93], 0, s[40:41]
	global_load_lds_dwordx4 v[92:93], off
	s_add_u32 m0, m0, 0x1000
	v_lshl_add_u64 v[92:93], v[92:93], 0, s[40:41]
	global_load_lds_dwordx4 v[92:93], off
	s_add_u32 m0, m0, 0x1000
	s_nop 0
	global_load_lds_dwordx4 v[90:91], off
	s_add_u32 m0, m0, 0x1000
	v_lshl_add_u64 v[90:91], v[90:91], 0, s[40:41]
	global_load_lds_dwordx4 v[90:91], off
	s_add_u32 m0, m0, 0x1000
	v_lshl_add_u64 v[90:91], v[90:91], 0, s[40:41]
	global_load_lds_dwordx4 v[90:91], off
	s_add_u32 m0, m0, 0x1000
	v_lshl_add_u64 v[90:91], v[90:91], 0, s[40:41]
	global_load_lds_dwordx4 v[90:91], off
	s_branch .LBB0_131
